# grid barrier: non-leader workgroups spin on the global generation word directly instead of waiting for their XCD leader to re-publish a per-XCD generation
# baseline (speedup 1.0000x reference)
; __device__ __forceinline__ unsigned xb_ld(unsigned* q)              { return __hip_atomic_load(q, __ATOMIC_RELAXED, __HIP_MEMORY_SCOPE_AGENT); }
; __device__ __forceinline__ unsigned xb_add(unsigned* q, unsigned v) { return __hip_atomic_fetch_add(q, v, __ATOMIC_RELAXED, __HIP_MEMORY_SCOPE_AGENT); }
; #define XB_SPIN(cond, bar) do { unsigned _sp = 0; while (cond) { __builtin_amdgcn_s_sleep(1); \
;     if ((++_sp & 255u) == 0u) { if (xb_ld(&(bar)[XB_TMO])) break; if (_sp > XB_SPIN_CAP) { atomicAdd(&(bar)[XB_TMO], 1u); break; } } } } while (0)
; __device__ __forceinline__ void xcd_barrier(const XcdBarrier& b) {
;     ...
;         const unsigned old = xb_add(&bar[XB_XSUB(b.x)], 1u);
;         const unsigned gen = old / nloc;
;         if (old + 1u == (gen + 1u) * nloc) {
;             __builtin_amdgcn_fence(__ATOMIC_RELEASE, "agent");
;             asm volatile("s_waitcnt vmcnt(0)" ::: "memory");
;             const unsigned og = xb_add(&bar[XB_TOP], 1u);
;             const unsigned tg = og / nx;
;             if (og + 1u == (tg + 1u) * nx) xb_add(&bar[XB_TOPGEN], 1u);
;             else XB_SPIN(xb_ld(&bar[XB_TOPGEN]) == tg, bar);
;             __builtin_amdgcn_fence(__ATOMIC_ACQUIRE, "agent");
;             xb_add(&bar[XB_XGEN(b.x)], 1u);
;             asm volatile("s_waitcnt vmcnt(0)" ::: "memory");
;         } else {
;             XB_SPIN(xb_ld(&bar[XB_XGEN(b.x)]) == gen, bar);
.LBB0_1096:
	v_readlane_b32 s12, v254, 57
	v_readlane_b32 s13, v254, 58
	v_cvt_f32_u32_e32 v0, v3
	v_sub_u32_e32 v9, 0, v3
	v_rcp_iflag_f32_e32 v0, v0
	s_nop 1
	global_atomic_add v8, v1, v203, s[12:13] sc0
	v_mul_f32_e32 v0, 0x4f7ffffe, v0
	v_cvt_u32_f32_e32 v0, v0
	v_mul_lo_u32 v9, v9, v0
	v_mul_hi_u32 v9, v0, v9
	v_add_u32_e32 v0, v0, v9
	s_waitcnt vmcnt(0)
	v_mul_hi_u32 v0, v8, v0
	v_mul_lo_u32 v9, v0, v3
	v_sub_u32_e32 v9, v8, v9
	v_add_u32_e32 v10, 1, v0
	v_cmp_ge_u32_e32 vcc, v9, v3
	v_add_u32_e32 v8, 1, v8
	s_nop 0
	v_cndmask_b32_e32 v0, v0, v10, vcc
	v_sub_u32_e32 v10, v9, v3
	v_cndmask_b32_e32 v9, v9, v10, vcc
	v_add_u32_e32 v10, 1, v0
	v_cmp_ge_u32_e32 vcc, v9, v3
	s_nop 1
	v_cndmask_b32_e32 v0, v0, v10, vcc
	v_mul_lo_u32 v9, v3, v0
	v_add_u32_e32 v3, v9, v3
	v_cmp_ne_u32_e32 vcc, v8, v3
	s_and_saveexec_b64 s[12:13], vcc
	s_xor_b64 s[12:13], exec, s[12:13]
	s_cbranch_execz .LBB0_1110
	v_readlane_b32 s14, v254, 63
	v_readlane_b32 s15, v255, 0
	s_waitcnt lgkmcnt(0)
	s_nop 3
	global_load_dword v2, v1, s[14:15] sc1
	s_waitcnt vmcnt(0)
	v_cmp_eq_u32_e32 vcc, v2, v0
	s_and_saveexec_b64 s[18:19], vcc
	s_cbranch_execz .LBB0_1109
	s_mov_b32 s26, 1
	s_mov_b64 s[20:21], 0
	s_branch .LBB0_1100
